# conv phase small GEMM (mi/mf/sdt columns): serial load-wait-mfma chain replaced by a 3-deep ring of 2-k-step blocks with immediate offsets and counted waits
# baseline (speedup 1.0000x reference)
;     DI bf16_t* fXN() const { return (bf16_t*)(ws + WS_XN); }
;     DI bf16_t* fWIN() const { return (bf16_t*)(ws + WS_WIN); }
; DI void phase_conv(const Params& p, const Ctx& c, int l, int S) {
;     ...
;         for (int tile = blockIdx.x * 8 + wave; tile < TG / 16; tile += gridDim.x * 8) {
;             const bf16_t* ap = c.fXN() + (size_t)(tile * 16 + lr) * 1024 + lg * 8;
;             const bf16_t* bp0 = c.fWIN() + (size_t)(3072 + lr) * 1024 + lg * 8; const bf16_t* bp1 = bp0 + 16 * 1024;
;             f32x4 a0 = (f32x4){0.f, 0.f, 0.f, 0.f}, a1 = a0;
; #pragma unroll 8
;             for (int kk = 0; kk < 32; ++kk) { const bf16x8 av = *(const bf16x8*)(ap + kk * 32);
;                 a0 = __builtin_amdgcn_mfma_f32_16x16x32_bf16(av, *(const bf16x8*)(bp0 + kk * 32), a0, 0, 0, 0);
;                 a1 = __builtin_amdgcn_mfma_f32_16x16x32_bf16(av, *(const bf16x8*)(bp1 + kk * 32), a1, 0, 0, 0); }
.LBB0_207:
	v_add_co_u32_e32 v22, vcc, 0x1aa00000, v12
	s_nop 1
	v_addc_co_u32_e32 v23, vcc, 0, v13, vcc
	v_add_co_u32_e32 v20, vcc, 0x1aa08000, v12
	s_nop 1
	v_addc_co_u32_e32 v21, vcc, 0, v13, vcc
	global_load_dwordx4 v[138:141], v[18:19], off
	global_load_dwordx4 v[142:145], v[22:23], off
	global_load_dwordx4 v[146:149], v[20:21], off
	global_load_dwordx4 v[150:153], v[18:19], off offset:64
	global_load_dwordx4 v[154:157], v[22:23], off offset:64
	global_load_dwordx4 v[158:161], v[20:21], off offset:64
	global_load_dwordx4 v[162:165], v[18:19], off offset:128
	global_load_dwordx4 v[182:185], v[22:23], off offset:128
	global_load_dwordx4 v[186:189], v[20:21], off offset:128
	global_load_dwordx4 v[190:193], v[18:19], off offset:192
	global_load_dwordx4 v[194:197], v[22:23], off offset:192
	global_load_dwordx4 v[198:201], v[20:21], off offset:192
	global_load_dwordx4 v[216:219], v[18:19], off offset:256
	global_load_dwordx4 v[220:223], v[22:23], off offset:256
	global_load_dwordx4 v[224:227], v[20:21], off offset:256
	global_load_dwordx4 v[228:231], v[18:19], off offset:320
	global_load_dwordx4 v[232:235], v[22:23], off offset:320
	global_load_dwordx4 v[236:239], v[20:21], off offset:320
	s_waitcnt vmcnt(16)
	v_mfma_f32_16x16x32_bf16 v[2:5], v[138:141], v[142:145], v[2:5]
	s_waitcnt vmcnt(15)
	v_mfma_f32_16x16x32_bf16 v[6:9], v[138:141], v[146:149], v[6:9]
	s_waitcnt vmcnt(13)
	v_mfma_f32_16x16x32_bf16 v[2:5], v[150:153], v[154:157], v[2:5]
	s_waitcnt vmcnt(12)
	v_mfma_f32_16x16x32_bf16 v[6:9], v[150:153], v[158:161], v[6:9]
	global_load_dwordx4 v[138:141], v[18:19], off offset:384
	global_load_dwordx4 v[142:145], v[22:23], off offset:384
	global_load_dwordx4 v[146:149], v[20:21], off offset:384
	global_load_dwordx4 v[150:153], v[18:19], off offset:448
	global_load_dwordx4 v[154:157], v[22:23], off offset:448
	global_load_dwordx4 v[158:161], v[20:21], off offset:448
	s_waitcnt vmcnt(16)
	v_mfma_f32_16x16x32_bf16 v[2:5], v[162:165], v[182:185], v[2:5]
	s_waitcnt vmcnt(15)
	v_mfma_f32_16x16x32_bf16 v[6:9], v[162:165], v[186:189], v[6:9]
	s_waitcnt vmcnt(13)
	v_mfma_f32_16x16x32_bf16 v[2:5], v[190:193], v[194:197], v[2:5]
	s_waitcnt vmcnt(12)
	v_mfma_f32_16x16x32_bf16 v[6:9], v[190:193], v[198:201], v[6:9]
	global_load_dwordx4 v[162:165], v[18:19], off offset:512
	global_load_dwordx4 v[182:185], v[22:23], off offset:512
	global_load_dwordx4 v[186:189], v[20:21], off offset:512
	global_load_dwordx4 v[190:193], v[18:19], off offset:576
	global_load_dwordx4 v[194:197], v[22:23], off offset:576
	global_load_dwordx4 v[198:201], v[20:21], off offset:576
	s_waitcnt vmcnt(16)
	v_mfma_f32_16x16x32_bf16 v[2:5], v[216:219], v[220:223], v[2:5]
	s_waitcnt vmcnt(15)
	v_mfma_f32_16x16x32_bf16 v[6:9], v[216:219], v[224:227], v[6:9]
	s_waitcnt vmcnt(13)
	v_mfma_f32_16x16x32_bf16 v[2:5], v[228:231], v[232:235], v[2:5]
	s_waitcnt vmcnt(12)
	v_mfma_f32_16x16x32_bf16 v[6:9], v[228:231], v[236:239], v[6:9]
	global_load_dwordx4 v[216:219], v[18:19], off offset:640
	global_load_dwordx4 v[220:223], v[22:23], off offset:640
	global_load_dwordx4 v[224:227], v[20:21], off offset:640
	global_load_dwordx4 v[228:231], v[18:19], off offset:704
	global_load_dwordx4 v[232:235], v[22:23], off offset:704
	global_load_dwordx4 v[236:239], v[20:21], off offset:704
	s_waitcnt vmcnt(16)
	v_mfma_f32_16x16x32_bf16 v[2:5], v[138:141], v[142:145], v[2:5]
	s_waitcnt vmcnt(15)
	v_mfma_f32_16x16x32_bf16 v[6:9], v[138:141], v[146:149], v[6:9]
	s_waitcnt vmcnt(13)
	v_mfma_f32_16x16x32_bf16 v[2:5], v[150:153], v[154:157], v[2:5]
	s_waitcnt vmcnt(12)
	v_mfma_f32_16x16x32_bf16 v[6:9], v[150:153], v[158:161], v[6:9]
	global_load_dwordx4 v[138:141], v[18:19], off offset:768
	global_load_dwordx4 v[142:145], v[22:23], off offset:768
	global_load_dwordx4 v[146:149], v[20:21], off offset:768
	global_load_dwordx4 v[150:153], v[18:19], off offset:832
	global_load_dwordx4 v[154:157], v[22:23], off offset:832
	global_load_dwordx4 v[158:161], v[20:21], off offset:832
	s_waitcnt vmcnt(16)
	v_mfma_f32_16x16x32_bf16 v[2:5], v[162:165], v[182:185], v[2:5]
	s_waitcnt vmcnt(15)
	v_mfma_f32_16x16x32_bf16 v[6:9], v[162:165], v[186:189], v[6:9]
	s_waitcnt vmcnt(13)
	v_mfma_f32_16x16x32_bf16 v[2:5], v[190:193], v[194:197], v[2:5]
	s_waitcnt vmcnt(12)
	v_mfma_f32_16x16x32_bf16 v[6:9], v[190:193], v[198:201], v[6:9]
	global_load_dwordx4 v[162:165], v[18:19], off offset:896
	global_load_dwordx4 v[182:185], v[22:23], off offset:896
	global_load_dwordx4 v[186:189], v[20:21], off offset:896
	global_load_dwordx4 v[190:193], v[18:19], off offset:960
	global_load_dwordx4 v[194:197], v[22:23], off offset:960
	global_load_dwordx4 v[198:201], v[20:21], off offset:960
	s_waitcnt vmcnt(16)
	v_mfma_f32_16x16x32_bf16 v[2:5], v[216:219], v[220:223], v[2:5]
	s_waitcnt vmcnt(15)
	v_mfma_f32_16x16x32_bf16 v[6:9], v[216:219], v[224:227], v[6:9]
	s_waitcnt vmcnt(13)
	v_mfma_f32_16x16x32_bf16 v[2:5], v[228:231], v[232:235], v[2:5]
	s_waitcnt vmcnt(12)
	v_mfma_f32_16x16x32_bf16 v[6:9], v[228:231], v[236:239], v[6:9]
	global_load_dwordx4 v[216:219], v[18:19], off offset:1024
	global_load_dwordx4 v[220:223], v[22:23], off offset:1024
	global_load_dwordx4 v[224:227], v[20:21], off offset:1024
	global_load_dwordx4 v[228:231], v[18:19], off offset:1088
	global_load_dwordx4 v[232:235], v[22:23], off offset:1088
	global_load_dwordx4 v[236:239], v[20:21], off offset:1088
	s_waitcnt vmcnt(16)
	v_mfma_f32_16x16x32_bf16 v[2:5], v[138:141], v[142:145], v[2:5]
	s_waitcnt vmcnt(15)
	v_mfma_f32_16x16x32_bf16 v[6:9], v[138:141], v[146:149], v[6:9]
	s_waitcnt vmcnt(13)
	v_mfma_f32_16x16x32_bf16 v[2:5], v[150:153], v[154:157], v[2:5]
	s_waitcnt vmcnt(12)
;     DI float* fSMALL() const { return (float*)(ws + WS_SMALL); }
; DI void phase_conv(const Params& p, const Ctx& c, int l, int S) {
;     ...
;             for (int kk = 0; kk < 32; ++kk) { const bf16x8 av = *(const bf16x8*)(ap + kk * 32);
;                 a0 = __builtin_amdgcn_mfma_f32_16x16x32_bf16(av, *(const bf16x8*)(bp0 + kk * 32), a0, 0, 0, 0);
;                 a1 = __builtin_amdgcn_mfma_f32_16x16x32_bf16(av, *(const bf16x8*)(bp1 + kk * 32), a1, 0, 0, 0); }
;             float* sp = c.fSMALL() + (size_t)(tile * 16 + lg * 4) * 32 + lr;
; #pragma unroll
;             for (int r = 0; r < 4; ++r) { sp[r * 32] = a0[r]; sp[r * 32 + 16] = a1[r]; }
	v_mfma_f32_16x16x32_bf16 v[6:9], v[150:153], v[158:161], v[6:9]
	global_load_dwordx4 v[138:141], v[18:19], off offset:1152
	global_load_dwordx4 v[142:145], v[22:23], off offset:1152
	global_load_dwordx4 v[146:149], v[20:21], off offset:1152
	global_load_dwordx4 v[150:153], v[18:19], off offset:1216
	global_load_dwordx4 v[154:157], v[22:23], off offset:1216
	global_load_dwordx4 v[158:161], v[20:21], off offset:1216
	s_waitcnt vmcnt(16)
	v_mfma_f32_16x16x32_bf16 v[2:5], v[162:165], v[182:185], v[2:5]
	s_waitcnt vmcnt(15)
	v_mfma_f32_16x16x32_bf16 v[6:9], v[162:165], v[186:189], v[6:9]
	s_waitcnt vmcnt(13)
	v_mfma_f32_16x16x32_bf16 v[2:5], v[190:193], v[194:197], v[2:5]
	s_waitcnt vmcnt(12)
	v_mfma_f32_16x16x32_bf16 v[6:9], v[190:193], v[198:201], v[6:9]
	global_load_dwordx4 v[162:165], v[18:19], off offset:1280
	global_load_dwordx4 v[182:185], v[22:23], off offset:1280
	global_load_dwordx4 v[186:189], v[20:21], off offset:1280
	global_load_dwordx4 v[190:193], v[18:19], off offset:1344
	global_load_dwordx4 v[194:197], v[22:23], off offset:1344
	global_load_dwordx4 v[198:201], v[20:21], off offset:1344
	s_waitcnt vmcnt(16)
	v_mfma_f32_16x16x32_bf16 v[2:5], v[216:219], v[220:223], v[2:5]
	s_waitcnt vmcnt(15)
	v_mfma_f32_16x16x32_bf16 v[6:9], v[216:219], v[224:227], v[6:9]
	s_waitcnt vmcnt(13)
	v_mfma_f32_16x16x32_bf16 v[2:5], v[228:231], v[232:235], v[2:5]
	s_waitcnt vmcnt(12)
	v_mfma_f32_16x16x32_bf16 v[6:9], v[228:231], v[236:239], v[6:9]
	global_load_dwordx4 v[216:219], v[18:19], off offset:1408
	global_load_dwordx4 v[220:223], v[22:23], off offset:1408
	global_load_dwordx4 v[224:227], v[20:21], off offset:1408
	global_load_dwordx4 v[228:231], v[18:19], off offset:1472
	global_load_dwordx4 v[232:235], v[22:23], off offset:1472
	global_load_dwordx4 v[236:239], v[20:21], off offset:1472
	s_waitcnt vmcnt(16)
	v_mfma_f32_16x16x32_bf16 v[2:5], v[138:141], v[142:145], v[2:5]
	s_waitcnt vmcnt(15)
	v_mfma_f32_16x16x32_bf16 v[6:9], v[138:141], v[146:149], v[6:9]
	s_waitcnt vmcnt(13)
	v_mfma_f32_16x16x32_bf16 v[2:5], v[150:153], v[154:157], v[2:5]
	s_waitcnt vmcnt(12)
	v_mfma_f32_16x16x32_bf16 v[6:9], v[150:153], v[158:161], v[6:9]
	global_load_dwordx4 v[138:141], v[18:19], off offset:1536
	global_load_dwordx4 v[142:145], v[22:23], off offset:1536
	global_load_dwordx4 v[146:149], v[20:21], off offset:1536
	global_load_dwordx4 v[150:153], v[18:19], off offset:1600
	global_load_dwordx4 v[154:157], v[22:23], off offset:1600
	global_load_dwordx4 v[158:161], v[20:21], off offset:1600
	s_waitcnt vmcnt(16)
	v_mfma_f32_16x16x32_bf16 v[2:5], v[162:165], v[182:185], v[2:5]
	s_waitcnt vmcnt(15)
	v_mfma_f32_16x16x32_bf16 v[6:9], v[162:165], v[186:189], v[6:9]
	s_waitcnt vmcnt(13)
	v_mfma_f32_16x16x32_bf16 v[2:5], v[190:193], v[194:197], v[2:5]
	s_waitcnt vmcnt(12)
	v_mfma_f32_16x16x32_bf16 v[6:9], v[190:193], v[198:201], v[6:9]
	global_load_dwordx4 v[162:165], v[18:19], off offset:1664
	global_load_dwordx4 v[182:185], v[22:23], off offset:1664
	global_load_dwordx4 v[186:189], v[20:21], off offset:1664
	global_load_dwordx4 v[190:193], v[18:19], off offset:1728
	global_load_dwordx4 v[194:197], v[22:23], off offset:1728
	global_load_dwordx4 v[198:201], v[20:21], off offset:1728
	s_waitcnt vmcnt(16)
	v_mfma_f32_16x16x32_bf16 v[2:5], v[216:219], v[220:223], v[2:5]
	s_waitcnt vmcnt(15)
	v_mfma_f32_16x16x32_bf16 v[6:9], v[216:219], v[224:227], v[6:9]
	s_waitcnt vmcnt(13)
	v_mfma_f32_16x16x32_bf16 v[2:5], v[228:231], v[232:235], v[2:5]
	s_waitcnt vmcnt(12)
	v_mfma_f32_16x16x32_bf16 v[6:9], v[228:231], v[236:239], v[6:9]
	global_load_dwordx4 v[216:219], v[18:19], off offset:1792
	global_load_dwordx4 v[220:223], v[22:23], off offset:1792
	global_load_dwordx4 v[224:227], v[20:21], off offset:1792
	global_load_dwordx4 v[228:231], v[18:19], off offset:1856
	global_load_dwordx4 v[232:235], v[22:23], off offset:1856
	global_load_dwordx4 v[236:239], v[20:21], off offset:1856
	s_waitcnt vmcnt(16)
	v_mfma_f32_16x16x32_bf16 v[2:5], v[138:141], v[142:145], v[2:5]
	s_waitcnt vmcnt(15)
	v_mfma_f32_16x16x32_bf16 v[6:9], v[138:141], v[146:149], v[6:9]
	s_waitcnt vmcnt(13)
	v_mfma_f32_16x16x32_bf16 v[2:5], v[150:153], v[154:157], v[2:5]
	s_waitcnt vmcnt(12)
	v_mfma_f32_16x16x32_bf16 v[6:9], v[150:153], v[158:161], v[6:9]
	global_load_dwordx4 v[138:141], v[18:19], off offset:1920
	global_load_dwordx4 v[142:145], v[22:23], off offset:1920
	global_load_dwordx4 v[146:149], v[20:21], off offset:1920
	global_load_dwordx4 v[150:153], v[18:19], off offset:1984
	global_load_dwordx4 v[154:157], v[22:23], off offset:1984
	global_load_dwordx4 v[158:161], v[20:21], off offset:1984
	s_waitcnt vmcnt(16)
	v_mfma_f32_16x16x32_bf16 v[2:5], v[162:165], v[182:185], v[2:5]
	s_waitcnt vmcnt(15)
	v_mfma_f32_16x16x32_bf16 v[6:9], v[162:165], v[186:189], v[6:9]
	s_waitcnt vmcnt(13)
	v_mfma_f32_16x16x32_bf16 v[2:5], v[190:193], v[194:197], v[2:5]
	s_waitcnt vmcnt(12)
	v_mfma_f32_16x16x32_bf16 v[6:9], v[190:193], v[198:201], v[6:9]
	s_waitcnt vmcnt(10)
	v_mfma_f32_16x16x32_bf16 v[2:5], v[216:219], v[220:223], v[2:5]
	s_waitcnt vmcnt(9)
	v_mfma_f32_16x16x32_bf16 v[6:9], v[216:219], v[224:227], v[6:9]
	s_waitcnt vmcnt(7)
	v_mfma_f32_16x16x32_bf16 v[2:5], v[228:231], v[232:235], v[2:5]
	s_waitcnt vmcnt(6)
	v_mfma_f32_16x16x32_bf16 v[6:9], v[228:231], v[236:239], v[6:9]
	s_waitcnt vmcnt(4)
	v_mfma_f32_16x16x32_bf16 v[2:5], v[138:141], v[142:145], v[2:5]
	s_waitcnt vmcnt(3)
	v_mfma_f32_16x16x32_bf16 v[6:9], v[138:141], v[146:149], v[6:9]
	s_waitcnt vmcnt(1)
	v_mfma_f32_16x16x32_bf16 v[2:5], v[150:153], v[154:157], v[2:5]
	s_waitcnt vmcnt(0)
	v_mfma_f32_16x16x32_bf16 v[6:9], v[150:153], v[158:161], v[6:9]
	v_lshl_or_b32 v18, s2, 4, v1
	v_ashrrev_i32_e32 v19, 31, v18
	v_lshlrev_b64 v[18:19], 7, v[18:19]
	s_add_i32 s2, s2, s81
	v_lshl_add_u64 v[18:19], v[10:11], 0, v[18:19]
	s_cmpk_gt_i32 s2, 0x7ff
	v_add_u32_e32 v16, s91, v16
	global_store_dword v[18:19], v2, off
	global_store_dword v[18:19], v6, off offset:64
	global_store_dword v[18:19], v3, off offset:128
	global_store_dword v[18:19], v7, off offset:192
	global_store_dword v[18:19], v4, off offset:256
	global_store_dword v[18:19], v8, off offset:320
	global_store_dword v[18:19], v5, off offset:384
	global_store_dword v[18:19], v9, off offset:448
	s_cbranch_scc0 .LBB0_206
